# up-GEMM epilogue: ACT/RAW streaming stores issued with the nt cache policy (on top of the up-GEMM load-segment recipe)
# baseline (speedup 1.0000x reference)
;     __device__ __forceinline__ void operator()(const f32x4 (&acc)[2][2][4][2], const Unit& u, int wr, int wc, int fr, int fq) const {
;         const int rbase = u.pm * BM + wr * 64 + 4 * fr;
;         float rs[2][4];
; #pragma unroll
;         for (int ai = 0; ai < 2; ++ai) { const f32x4 sv = *(const f32x4*)(ss + rbase + ai * HALF);
; #pragma unroll
;             for (int m = 0; m < 4; ++m) rs[ai][m] = __builtin_amdgcn_rsqf(sv[m] * (1.0f / DM) + EPS); }
;         u32x2 keep[2][4];
; #pragma unroll
;         for (int n = 0; n < 2; ++n) {
;             const int ci = wc * 32 + 8 * fq + 4 * n, cgc = u.pn * HALF + ci;
;             const f32x4 g0 = *(const f32x4*)(cw + cgc), g1 = *(const f32x4*)(cw + NUP + cgc), g2 = *(const f32x4*)(cw + 2 * NUP + cgc), gb = *(const f32x4*)(cb + cgc);
;             const f32x4 v0 = *(const f32x4*)(cw + DFF + cgc), v1 = *(const f32x4*)(cw + NUP + DFF + cgc), v2 = *(const f32x4*)(cw + 2 * NUP + DFF + cgc), vb = *(const f32x4*)(cb + DFF + cgc);
; #pragma unroll
;             for (int ai = 0; ai < 2; ++ai) {
;                 float* rawp = RAW + ((size_t)(u.pm * 4 + ai * 2 + wr) * 4) * NUP + u.pn * BM + ci;
;                 f32x4 G[4], V[4];
; #pragma unroll
;                 for (int m = 0; m < 4; ++m) { G[m] = acc[ai][0][m][n] * rs[ai][m]; V[m] = acc[ai][1][m][n] * rs[ai][m]; }
;                 f32x4 G3s, G2s, V3s, V2s;
; #pragma unroll
;                 for (int e = 0; e < 4; ++e) { G3s[e] = dppz<0x111>(G[3][e]); G2s[e] = dppz<0x111>(G[2][e]); V3s[e] = dppz<0x111>(V[3][e]); V2s[e] = dppz<0x111>(V[2][e]); }
;                 f32x4 cg[4], cv[4];
;                 cg[0] = gb + g0 * G2s + g1 * G3s + g2 * G[0]; cv[0] = vb + v0 * V2s + v1 * V3s + v2 * V[0];
;                 cg[1] = gb + g0 * G3s + g1 * G[0] + g2 * G[1]; cv[1] = vb + v0 * V3s + v1 * V[0] + v2 * V[1];
;                 cg[2] = gb + g0 * G[0] + g1 * G[1] + g2 * G[2]; cv[2] = vb + v0 * V[0] + v1 * V[1] + v2 * V[2];
;                 cg[3] = gb + g0 * G[1] + g1 * G[2] + g2 * G[3]; cv[3] = vb + v0 * V[1] + v1 * V[2] + v2 * V[3];
; #pragma unroll
;                 for (int m = 0; m < 4; ++m) {
;                     const f32x2 a01 = silu_mul_pk((f32x2){cg[m][0], cg[m][1]}, (f32x2){cv[m][0], cv[m][1]}), a23 = silu_mul_pk((f32x2){cg[m][2], cg[m][3]}, (f32x2){cv[m][2], cv[m][3]});
.LBB0_971:
	v_lshl_add_u32 v186, s58, 8, v229
	v_ashrrev_i32_e32 v187, 31, v186
	v_lshl_add_u64 v[108:109], v[186:187], 2, s[38:39]
	global_load_dwordx4 v[104:107], v[108:109], off
	global_load_dwordx4 v[144:147], v[108:109], off offset:512
	s_lshl_b32 s54, s36, 7
	s_lshl_b32 s41, s58, 2
	s_add_i32 s41, s41, s73
	s_lshl_b32 s42, s36, 8
	s_ashr_i32 s43, s42, 31
	s_mul_i32 s48, s41, 0x2c000
	s_mul_hi_i32 s36, s41, 0x2c000
	s_add_u32 s48, s5, s48
	s_addc_u32 s36, s87, s36
	s_lshl_b64 s[56:57], s[42:43], 2
	s_add_u32 s42, s48, s56
	s_addc_u32 s43, s36, s57
	v_cmp_lt_i32_e32 vcc, 14, v227
	s_mov_b64 s[48:49], 0
	s_waitcnt vmcnt(0)
	v_fmamk_f32 v104, v104, 0x3a000000, v220
	v_rsq_f32_e32 v204, v104
	v_fmamk_f32 v104, v105, 0x3a000000, v220
	v_rsq_f32_e32 v188, v104
	v_fmamk_f32 v104, v106, 0x3a000000, v220
	v_rsq_f32_e32 v202, v104
	v_fmamk_f32 v104, v107, 0x3a000000, v220
	v_rsq_f32_e32 v200, v104
	v_add_u32_e32 v104, s54, v180
	v_ashrrev_i32_e32 v105, 31, v104
	v_lshlrev_b64 v[132:133], 2, v[104:105]
	v_lshl_add_u64 v[206:207], s[12:13], 0, v[132:133]
	v_lshl_add_u64 v[208:209], s[14:15], 0, v[132:133]
	global_load_dwordx4 v[104:107], v[206:207], off
	v_lshl_add_u64 v[108:109], s[16:17], 0, v[132:133]
	global_load_dwordx4 v[120:123], v[208:209], off
	v_lshl_add_u64 v[112:113], s[18:19], 0, v[132:133]
	global_load_dwordx4 v[108:111], v[108:109], off
	v_lshl_add_u64 v[116:117], s[28:29], 0, v[132:133]
	global_load_dwordx4 v[112:115], v[112:113], off
	v_mov_b32_e32 v203, v202
	global_load_dwordx4 v[124:127], v[116:117], off
	v_lshl_add_u64 v[116:117], s[44:45], 0, v[132:133]
	global_load_dwordx4 v[128:131], v[116:117], off
	v_lshl_add_u64 v[116:117], s[46:47], 0, v[132:133]
	v_lshl_add_u64 v[132:133], s[66:67], 0, v[132:133]
	global_load_dwordx4 v[132:135], v[132:133], off
	v_pk_mul_f32 v[140:141], v[140:141], v[202:203] op_sel_hi:[1,0]
	global_load_dwordx4 v[116:119], v[116:117], off
	v_mov_b32_e32 v201, v200
	v_pk_mul_f32 v[164:165], v[100:101], v[200:201] op_sel_hi:[1,0]
	v_pk_mul_f32 v[170:171], v[98:99], v[200:201] op_sel_hi:[1,0]
	v_mov_b32_dpp v98, v140 row_shr:1 row_mask:0xf bank_mask:0xf bound_ctrl:1
	v_mov_b32_dpp v99, v141 row_shr:1 row_mask:0xf bank_mask:0xf bound_ctrl:1
	v_mov_b32_e32 v205, v204
	v_pk_mul_f32 v[168:169], v[96:97], v[200:201] op_sel_hi:[1,0]
	v_mov_b32_dpp v96, v164 row_shr:1 row_mask:0xf bank_mask:0xf bound_ctrl:1
	v_mov_b32_dpp v97, v165 row_shr:1 row_mask:0xf bank_mask:0xf bound_ctrl:1
	v_pk_mul_f32 v[160:161], v[160:161], v[204:205] op_sel_hi:[1,0]
	v_pk_mul_f32 v[142:143], v[142:143], v[202:203] op_sel_hi:[1,0]
	v_pk_mul_f32 v[136:137], v[136:137], v[202:203] op_sel_hi:[1,0]
	v_pk_mul_f32 v[166:167], v[102:103], v[200:201] op_sel_hi:[1,0]
	v_mov_b32_dpp v218, v142 row_shr:1 row_mask:0xf bank_mask:0xf bound_ctrl:1
	v_mov_b32_dpp v102, v136 row_shr:1 row_mask:0xf bank_mask:0xf bound_ctrl:1
	v_mov_b32_dpp v103, v137 row_shr:1 row_mask:0xf bank_mask:0xf bound_ctrl:1
	v_mov_b32_dpp v219, v143 row_shr:1 row_mask:0xf bank_mask:0xf bound_ctrl:1
	v_mov_b32_dpp v100, v168 row_shr:1 row_mask:0xf bank_mask:0xf bound_ctrl:1
	v_mov_b32_dpp v101, v169 row_shr:1 row_mask:0xf bank_mask:0xf bound_ctrl:1
	v_mov_b32_dpp v210, v166 row_shr:1 row_mask:0xf bank_mask:0xf bound_ctrl:1
	v_mov_b32_dpp v211, v167 row_shr:1 row_mask:0xf bank_mask:0xf bound_ctrl:1
	v_pk_mul_f32 v[162:163], v[162:163], v[204:205] op_sel_hi:[1,0]
	v_pk_mul_f32 v[156:157], v[156:157], v[204:205] op_sel_hi:[1,0]
	v_pk_mul_f32 v[138:139], v[138:139], v[202:203] op_sel_hi:[1,0]
	v_mov_b32_e32 v189, v188
	v_mov_b32_dpp v232, v170 row_shr:1 row_mask:0xf bank_mask:0xf bound_ctrl:1
	v_mov_b32_dpp v234, v138 row_shr:1 row_mask:0xf bank_mask:0xf bound_ctrl:1
	v_mov_b32_dpp v235, v139 row_shr:1 row_mask:0xf bank_mask:0xf bound_ctrl:1
	v_mov_b32_dpp v233, v171 row_shr:1 row_mask:0xf bank_mask:0xf bound_ctrl:1
	v_pk_mul_f32 v[158:159], v[158:159], v[204:205] op_sel_hi:[1,0]
	v_pk_mul_f32 v[152:153], v[152:153], v[188:189] op_sel_hi:[1,0]
	v_pk_mul_f32 v[154:155], v[154:155], v[188:189] op_sel_hi:[1,0]
	v_pk_mul_f32 v[148:149], v[148:149], v[188:189] op_sel_hi:[1,0]
	v_pk_mul_f32 v[150:151], v[150:151], v[188:189] op_sel_hi:[1,0]
	v_mov_b32_e32 v212, v204
	v_mov_b32_e32 v213, v204
	v_mov_b32_e32 v190, v188
	v_mov_b32_e32 v191, v188
	v_mov_b32_e32 v214, v202
	v_mov_b32_e32 v215, v202
	v_mov_b32_e32 v216, v200
	v_mov_b32_e32 v217, v200
	s_waitcnt vmcnt(6)
	v_pk_fma_f32 v[98:99], v[104:105], v[98:99], v[120:121]
	v_pk_fma_f32 v[218:219], v[106:107], v[218:219], v[122:123]
	s_waitcnt vmcnt(5)
	v_pk_fma_f32 v[98:99], v[108:109], v[96:97], v[98:99]
	v_pk_fma_f32 v[218:219], v[110:111], v[210:211], v[218:219]
	s_waitcnt vmcnt(4)
	v_pk_fma_f32 v[98:99], v[112:113], v[160:161], v[98:99]
	v_pk_fma_f32 v[218:219], v[114:115], v[162:163], v[218:219]
	v_pk_mul_f32 v[252:253], v[98:99], s[86:87] op_sel_hi:[1,0]
	v_pk_fma_f32 v[96:97], v[104:105], v[96:97], v[120:121]
	v_exp_f32_e32 v252, v252
	v_exp_f32_e32 v253, v253
	v_pk_fma_f32 v[96:97], v[108:109], v[160:161], v[96:97]
	s_waitcnt vmcnt(1)
	v_pk_fma_f32 v[102:103], v[124:125], v[102:103], v[132:133]
	v_pk_fma_f32 v[234:235], v[126:127], v[234:235], v[134:135]
	v_pk_add_f32 v[252:253], v[252:253], 1.0 op_sel_hi:[1,0]
	v_pk_fma_f32 v[102:103], v[128:129], v[100:101], v[102:103]
	v_rcp_f32_e32 v252, v252
	v_rcp_f32_e32 v253, v253
	s_waitcnt vmcnt(0)
; __device__ __forceinline__ unsigned cvt_pk_bf16(float lo, float hi) { unsigned r; asm volatile("v_cvt_pk_bf16_f32 %0, %1, %2" : "=v"(r) : "v"(lo), "v"(hi)); return r; }
;     __device__ __forceinline__ void operator()(const f32x4 (&acc)[2][2][4][2], const Unit& u, int wr, int wc, int fr, int fq) const {
;     ...
;                 f32x4 cg[4], cv[4];
;                 cg[0] = gb + g0 * G2s + g1 * G3s + g2 * G[0]; cv[0] = vb + v0 * V2s + v1 * V3s + v2 * V[0];
;                 cg[1] = gb + g0 * G3s + g1 * G[0] + g2 * G[1]; cv[1] = vb + v0 * V3s + v1 * V[0] + v2 * V[1];
;                 cg[2] = gb + g0 * G[0] + g1 * G[1] + g2 * G[2]; cv[2] = vb + v0 * V[0] + v1 * V[1] + v2 * V[2];
;                 cg[3] = gb + g0 * G[1] + g1 * G[2] + g2 * G[3]; cv[3] = vb + v0 * V[1] + v1 * V[2] + v2 * V[3];
; #pragma unroll
;                 for (int m = 0; m < 4; ++m) {
;                     const f32x2 a01 = silu_mul_pk((f32x2){cg[m][0], cg[m][1]}, (f32x2){cv[m][0], cv[m][1]}), a23 = silu_mul_pk((f32x2){cg[m][2], cg[m][3]}, (f32x2){cv[m][2], cv[m][3]});
;                     u32x2 w; w.x = cvt_pk_bf16(a01.x, a01.y); w.y = cvt_pk_bf16(a23.x, a23.y);
;                     if (n == 0) keep[ai][m] = w;
;                     else if (m >= 2 || fr != 0) { u32x4 o; o.x = keep[ai][m].x; o.y = keep[ai][m].y; o.z = w.x; o.w = w.y;
;                         *(u32x4*)(ACT + (size_t)(rbase + ai * HALF + m) * DFF + u.pn * HALF + wc * 32 + 8 * fq) = o; }
;                 }
;                 if (fr == 0) { *(f32x4*)(rawp) = G[0]; *(f32x4*)(rawp + HALF) = V[0]; *(f32x4*)(rawp + NUP) = G[1]; *(f32x4*)(rawp + NUP + HALF) = V[1]; }
;                 if (fr == 15) { *(f32x4*)(rawp + 2 * (size_t)NUP) = G[2]; *(f32x4*)(rawp + 2 * (size_t)NUP + HALF) = V[2]; *(f32x4*)(rawp + 3 * (size_t)NUP) = G[3]; *(f32x4*)(rawp + 3 * (size_t)NUP + HALF) = V[3]; }
	v_pk_fma_f32 v[102:103], v[156:157], v[116:117], v[102:103]
	v_pk_fma_f32 v[234:235], v[130:131], v[232:233], v[234:235]
	v_pk_fma_f32 v[238:239], v[112:113], v[152:153], v[96:97]
	v_pk_mul_f32 v[98:99], v[98:99], v[252:253]
	v_pk_fma_f32 v[234:235], v[158:159], v[118:119], v[234:235]
	v_pk_mul_f32 v[98:99], v[102:103], v[98:99]
	v_pk_mul_f32 v[102:103], v[218:219], s[86:87] op_sel_hi:[1,0]
	v_pk_fma_f32 v[210:211], v[106:107], v[210:211], v[122:123]
	v_exp_f32_e32 v102, v102
	v_exp_f32_e32 v103, v103
	v_pk_fma_f32 v[100:101], v[124:125], v[100:101], v[132:133]
	v_pk_fma_f32 v[210:211], v[110:111], v[162:163], v[210:211]
	v_pk_fma_f32 v[100:101], v[128:129], v[156:157], v[100:101]
	v_pk_add_f32 v[102:103], v[102:103], 1.0 op_sel_hi:[1,0]
	v_pk_fma_f32 v[236:237], v[114:115], v[154:155], v[210:211]
	v_rcp_f32_e32 v102, v102
	v_rcp_f32_e32 v103, v103
	v_pk_fma_f32 v[100:101], v[148:149], v[116:117], v[100:101]
	v_pk_fma_f32 v[96:97], v[126:127], v[232:233], v[134:135]
	v_pk_fma_f32 v[210:211], v[104:105], v[160:161], v[120:121]
	v_pk_mul_f32 v[102:103], v[218:219], v[102:103]
	v_pk_fma_f32 v[96:97], v[130:131], v[158:159], v[96:97]
	v_pk_mul_f32 v[218:219], v[234:235], v[102:103]
	v_cvt_pk_bf16_f32 v102, v98, v99
	v_pk_mul_f32 v[98:99], v[238:239], s[86:87] op_sel_hi:[1,0]
	v_pk_fma_f32 v[232:233], v[150:151], v[118:119], v[96:97]
	v_exp_f32_e32 v98, v98
	v_exp_f32_e32 v99, v99
	v_pk_fma_f32 v[96:97], v[106:107], v[162:163], v[122:123]
	v_pk_fma_f32 v[210:211], v[108:109], v[152:153], v[210:211]
	v_pk_fma_f32 v[96:97], v[110:111], v[154:155], v[96:97]
	v_pk_add_f32 v[98:99], v[98:99], 1.0 op_sel_hi:[1,0]
	v_pk_fma_f32 v[240:241], v[114:115], v[142:143], v[96:97]
	v_rcp_f32_e32 v98, v98
	v_rcp_f32_e32 v99, v99
	v_pk_fma_f32 v[242:243], v[112:113], v[140:141], v[210:211]
	v_cvt_pk_bf16_f32 v103, v218, v219
	v_pk_fma_f32 v[96:97], v[126:127], v[158:159], v[134:135]
	v_pk_mul_f32 v[98:99], v[238:239], v[98:99]
	v_pk_fma_f32 v[210:211], v[124:125], v[156:157], v[132:133]
	v_pk_mul_f32 v[98:99], v[100:101], v[98:99]
	v_pk_mul_f32 v[100:101], v[236:237], s[86:87] op_sel_hi:[1,0]
	v_pk_fma_f32 v[96:97], v[130:131], v[150:151], v[96:97]
	v_exp_f32_e32 v100, v100
	v_exp_f32_e32 v101, v101
	v_pk_fma_f32 v[210:211], v[128:129], v[148:149], v[210:211]
	v_pk_fma_f32 v[244:245], v[138:139], v[118:119], v[96:97]
	v_pk_fma_f32 v[96:97], v[106:107], v[154:155], v[122:123]
	v_pk_add_f32 v[100:101], v[100:101], 1.0 op_sel_hi:[1,0]
	v_pk_fma_f32 v[246:247], v[136:137], v[116:117], v[210:211]
	v_rcp_f32_e32 v100, v100
	v_rcp_f32_e32 v101, v101
	v_pk_fma_f32 v[210:211], v[104:105], v[152:153], v[120:121]
	v_pk_fma_f32 v[96:97], v[110:111], v[142:143], v[96:97]
	v_pk_fma_f32 v[210:211], v[108:109], v[140:141], v[210:211]
	v_pk_mul_f32 v[100:101], v[236:237], v[100:101]
	v_pk_fma_f32 v[96:97], v[114:115], v[166:167], v[96:97]
	v_pk_mul_f32 v[218:219], v[232:233], v[100:101]
	v_cvt_pk_bf16_f32 v100, v98, v99
	v_pk_mul_f32 v[98:99], v[242:243], s[86:87] op_sel_hi:[1,0]
	v_cvt_pk_bf16_f32 v101, v218, v219
	v_pk_mul_f32 v[218:219], v[240:241], s[86:87] op_sel_hi:[1,0]
	v_exp_f32_e32 v98, v98
	v_exp_f32_e32 v99, v99
	v_exp_f32_e32 v218, v218
	v_exp_f32_e32 v219, v219
	v_pk_fma_f32 v[248:249], v[112:113], v[164:165], v[210:211]
	v_pk_add_f32 v[98:99], v[98:99], 1.0 op_sel_hi:[1,0]
	v_pk_mul_f32 v[232:233], v[96:97], s[86:87] op_sel_hi:[1,0]
	v_pk_add_f32 v[218:219], v[218:219], 1.0 op_sel_hi:[1,0]
	v_rcp_f32_e32 v98, v98
	v_rcp_f32_e32 v99, v99
	v_rcp_f32_e32 v218, v218
	v_rcp_f32_e32 v219, v219
	v_exp_f32_e32 v232, v232
	v_pk_mul_f32 v[98:99], v[242:243], v[98:99]
	v_exp_f32_e32 v233, v233
	v_pk_mul_f32 v[218:219], v[240:241], v[218:219]
	v_pk_mul_f32 v[98:99], v[246:247], v[98:99]
	v_pk_mul_f32 v[218:219], v[244:245], v[218:219]
	v_cvt_pk_bf16_f32 v98, v98, v99
	v_pk_add_f32 v[232:233], v[232:233], 1.0 op_sel_hi:[1,0]
	v_cvt_pk_bf16_f32 v99, v218, v219
	v_pk_mul_f32 v[218:219], v[248:249], s[86:87] op_sel_hi:[1,0]
	v_rcp_f32_e32 v232, v232
	v_exp_f32_e32 v218, v218
	v_exp_f32_e32 v219, v219
	v_rcp_f32_e32 v233, v233
	v_pk_fma_f32 v[210:211], v[126:127], v[150:151], v[134:135]
	v_pk_fma_f32 v[250:251], v[124:125], v[148:149], v[132:133]
	v_pk_add_f32 v[218:219], v[218:219], 1.0 op_sel_hi:[1,0]
	v_pk_fma_f32 v[210:211], v[130:131], v[138:139], v[210:211]
	v_rcp_f32_e32 v218, v218
	v_rcp_f32_e32 v219, v219
	v_pk_fma_f32 v[250:251], v[128:129], v[136:137], v[250:251]
	v_pk_fma_f32 v[210:211], v[170:171], v[118:119], v[210:211]
	v_pk_mul_f32 v[96:97], v[96:97], v[232:233]
	v_pk_fma_f32 v[250:251], v[168:169], v[116:117], v[250:251]
	v_pk_mul_f32 v[218:219], v[248:249], v[218:219]
	v_pk_mul_f32 v[210:211], v[210:211], v[96:97]
	v_pk_mul_f32 v[218:219], v[250:251], v[218:219]
	s_nop 0
	v_cvt_pk_bf16_f32 v96, v218, v219
	v_cvt_pk_bf16_f32 v97, v210, v211
	v_lshl_add_u64 v[210:211], v[180:181], 2, s[42:43]
	s_and_saveexec_b64 s[42:43], vcc
	s_xor_b64 s[42:43], exec, s[42:43]
	s_cbranch_execz .LBB0_973
	v_add_co_u32_e32 v148, vcc, 0x16000, v210
	s_mov_b64 s[48:49], exec
	s_nop 0
	v_addc_co_u32_e32 v149, vcc, 0, v211, vcc
	global_store_dwordx4 v[148:149], v[140:143], off nt
.LBB0_973:
	s_or_saveexec_b64 s[42:43], s[42:43]
	s_nop 0
	v_mov_b64_e32 v[142:143], 0x16200
	v_mov_b64_e32 v[140:141], 0x21000
	v_mov_b64_e32 v[218:219], 0x21200
	s_xor_b64 exec, exec, s[42:43]
	s_cbranch_execz .LBB0_977
	v_cmp_eq_u32_e32 vcc, 0, v227
	s_mov_b64 s[58:59], s[48:49]
	s_and_saveexec_b64 s[60:61], vcc
	s_cbranch_execz .LBB0_976
	s_or_b64 s[58:59], s[48:49], exec
	global_store_dwordx4 v[210:211], v[160:163], off nt

;     __device__ __forceinline__ void operator()(const f32x4 (&acc)[2][2][4][2], const Unit& u, int wr, int wc, int fr, int fq) const {
;     ...
;         for (int ai = 0; ai < 2; ++ai) { const f32x4 sv = *(const f32x4*)(ss + rbase + ai * HALF);
; #pragma unroll
;             for (int m = 0; m < 4; ++m) rs[ai][m] = __builtin_amdgcn_rsqf(sv[m] * (1.0f / DM) + EPS); }
;         u32x2 keep[2][4];
; #pragma unroll
;         for (int n = 0; n < 2; ++n) {
;             const int ci = wc * 32 + 8 * fq + 4 * n, cgc = u.pn * HALF + ci;
;             const f32x4 g0 = *(const f32x4*)(cw + cgc), g1 = *(const f32x4*)(cw + NUP + cgc), g2 = *(const f32x4*)(cw + 2 * NUP + cgc), gb = *(const f32x4*)(cb + cgc);
;             const f32x4 v0 = *(const f32x4*)(cw + DFF + cgc), v1 = *(const f32x4*)(cw + NUP + DFF + cgc), v2 = *(const f32x4*)(cw + 2 * NUP + DFF + cgc), vb = *(const f32x4*)(cb + DFF + cgc);
; #pragma unroll
;             for (int ai = 0; ai < 2; ++ai) {
;                 float* rawp = RAW + ((size_t)(u.pm * 4 + ai * 2 + wr) * 4) * NUP + u.pn * BM + ci;
;                 f32x4 G[4], V[4];
; #pragma unroll
;                 for (int m = 0; m < 4; ++m) { G[m] = acc[ai][0][m][n] * rs[ai][m]; V[m] = acc[ai][1][m][n] * rs[ai][m]; }
;                 f32x4 G3s, G2s, V3s, V2s;
; #pragma unroll
;                 for (int e = 0; e < 4; ++e) { G3s[e] = dppz<0x111>(G[3][e]); G2s[e] = dppz<0x111>(G[2][e]); V3s[e] = dppz<0x111>(V[3][e]); V2s[e] = dppz<0x111>(V[2][e]); }
;                 f32x4 cg[4], cv[4];
;                 cg[0] = gb + g0 * G2s + g1 * G3s + g2 * G[0]; cv[0] = vb + v0 * V2s + v1 * V3s + v2 * V[0];
;                 cg[1] = gb + g0 * G3s + g1 * G[0] + g2 * G[1]; cv[1] = vb + v0 * V3s + v1 * V[0] + v2 * V[1];
;                 cg[2] = gb + g0 * G[0] + g1 * G[1] + g2 * G[2]; cv[2] = vb + v0 * V[0] + v1 * V[1] + v2 * V[2];
;                 cg[3] = gb + g0 * G[1] + g1 * G[2] + g2 * G[3]; cv[3] = vb + v0 * V[1] + v1 * V[2] + v2 * V[3];
; #pragma unroll
;                 for (int m = 0; m < 4; ++m) {
;     ...
;                 if (fr == 0) { *(f32x4*)(rawp) = G[0]; *(f32x4*)(rawp + HALF) = V[0]; *(f32x4*)(rawp + NUP) = G[1]; *(f32x4*)(rawp + NUP + HALF) = V[1]; }
;                 if (fr == 15) { *(f32x4*)(rawp + 2 * (size_t)NUP) = G[2]; *(f32x4*)(rawp + 2 * (size_t)NUP + HALF) = V[2]; *(f32x4*)(rawp + 3 * (size_t)NUP) = G[3]; *(f32x4*)(rawp + 3 * (size_t)NUP + HALF) = V[3]; }
.LBB0_977:
	s_or_b64 exec, exec, s[42:43]
	s_and_saveexec_b64 s[42:43], s[48:49]
	s_cbranch_execz .LBB0_979
	v_lshl_add_u64 v[142:143], v[210:211], 0, v[142:143]
	global_store_dwordx4 v[142:143], v[136:139], off nt
	s_nop 1
	v_lshl_add_u64 v[136:137], v[210:211], 0, v[140:141]
	global_store_dwordx4 v[136:137], v[164:167], off nt
	v_lshl_add_u64 v[136:137], v[210:211], 0, v[218:219]
	global_store_dwordx4 v[136:137], v[168:171], off nt
.LBB0_979:
	s_or_b64 exec, exec, s[42:43]
	v_fmamk_f32 v136, v144, 0x3a000000, v220
	v_rsq_f32_e32 v156, v136
	v_fmamk_f32 v136, v145, 0x3a000000, v220
	v_rsq_f32_e32 v148, v136
	v_fmamk_f32 v136, v146, 0x3a000000, v220
	v_rsq_f32_e32 v154, v136
	v_fmamk_f32 v136, v147, 0x3a000000, v220
	v_rsq_f32_e32 v152, v136
	v_mov_b32_e32 v157, v156
	v_mov_b32_e32 v155, v154
	v_pk_mul_f32 v[146:147], v[82:83], v[154:155] op_sel_hi:[1,0]
	v_mov_b32_e32 v153, v152
	v_pk_mul_f32 v[82:83], v[74:75], v[152:153] op_sel_hi:[1,0]
	v_mov_b32_dpp v74, v146 row_shr:1 row_mask:0xf bank_mask:0xf bound_ctrl:1
	v_mov_b32_dpp v75, v147 row_shr:1 row_mask:0xf bank_mask:0xf bound_ctrl:1
	v_pk_mul_f32 v[144:145], v[80:81], v[154:155] op_sel_hi:[1,0]
	v_pk_mul_f32 v[80:81], v[72:73], v[152:153] op_sel_hi:[1,0]
	v_mov_b32_dpp v72, v82 row_shr:1 row_mask:0xf bank_mask:0xf bound_ctrl:1
	v_mov_b32_dpp v73, v83 row_shr:1 row_mask:0xf bank_mask:0xf bound_ctrl:1
	v_pk_fma_f32 v[74:75], v[106:107], v[74:75], v[122:123]
	v_pk_mul_f32 v[94:95], v[94:95], v[156:157] op_sel_hi:[1,0]
	v_mov_b32_e32 v149, v148
	v_pk_mul_f32 v[142:143], v[66:67], v[152:153] op_sel_hi:[1,0]
	v_pk_fma_f32 v[74:75], v[110:111], v[72:73], v[74:75]
	v_pk_fma_f32 v[72:73], v[106:107], v[72:73], v[122:123]
	v_pk_mul_f32 v[90:91], v[90:91], v[148:149] op_sel_hi:[1,0]
	v_pk_mul_f32 v[138:139], v[78:79], v[148:149] op_sel_hi:[1,0]
	v_pk_mul_f32 v[78:79], v[70:71], v[154:155] op_sel_hi:[1,0]
	v_mov_b32_dpp v164, v142 row_shr:1 row_mask:0xf bank_mask:0xf bound_ctrl:1
	v_mov_b32_dpp v165, v143 row_shr:1 row_mask:0xf bank_mask:0xf bound_ctrl:1
	v_pk_fma_f32 v[72:73], v[110:111], v[94:95], v[72:73]
	v_pk_mul_f32 v[86:87], v[86:87], v[156:157] op_sel_hi:[1,0]
	v_mov_b32_dpp v166, v78 row_shr:1 row_mask:0xf bank_mask:0xf bound_ctrl:1
	v_mov_b32_dpp v167, v79 row_shr:1 row_mask:0xf bank_mask:0xf bound_ctrl:1
	v_pk_fma_f32 v[168:169], v[114:115], v[90:91], v[72:73]
	v_pk_fma_f32 v[72:73], v[126:127], v[164:165], v[134:135]
	v_pk_fma_f32 v[166:167], v[126:127], v[166:167], v[134:135]
	v_pk_fma_f32 v[72:73], v[130:131], v[86:87], v[72:73]
	v_pk_fma_f32 v[166:167], v[130:131], v[164:165], v[166:167]
	v_pk_fma_f32 v[164:165], v[118:119], v[138:139], v[72:73]
	v_pk_fma_f32 v[72:73], v[106:107], v[94:95], v[122:123]
	v_mov_b32_dpp v66, v144 row_shr:1 row_mask:0xf bank_mask:0xf bound_ctrl:1
	v_pk_fma_f32 v[72:73], v[110:111], v[90:91], v[72:73]
	v_mov_b32_dpp v67, v145 row_shr:1 row_mask:0xf bank_mask:0xf bound_ctrl:1
	v_pk_fma_f32 v[218:219], v[114:115], v[146:147], v[72:73]
	v_pk_fma_f32 v[72:73], v[126:127], v[86:87], v[134:135]
	v_pk_mul_f32 v[140:141], v[64:65], v[152:153] op_sel_hi:[1,0]
	v_pk_fma_f32 v[72:73], v[130:131], v[138:139], v[72:73]
	v_mov_b32_dpp v64, v80 row_shr:1 row_mask:0xf bank_mask:0xf bound_ctrl:1
	v_pk_fma_f32 v[234:235], v[118:119], v[78:79], v[72:73]
	v_pk_fma_f32 v[72:73], v[106:107], v[90:91], v[122:123]
	v_mov_b32_dpp v65, v81 row_shr:1 row_mask:0xf bank_mask:0xf bound_ctrl:1
	v_pk_fma_f32 v[66:67], v[104:105], v[66:67], v[120:121]
	v_pk_fma_f32 v[72:73], v[110:111], v[146:147], v[72:73]
	v_pk_mul_f32 v[92:93], v[92:93], v[156:157] op_sel_hi:[1,0]
	v_pk_fma_f32 v[66:67], v[108:109], v[64:65], v[66:67]
	v_pk_fma_f32 v[106:107], v[114:115], v[82:83], v[72:73]
	v_pk_fma_f32 v[72:73], v[126:127], v[138:139], v[134:135]
	v_pk_fma_f32 v[66:67], v[112:113], v[92:93], v[66:67]
	v_pk_fma_f32 v[72:73], v[130:131], v[78:79], v[72:73]
	v_pk_mul_f32 v[136:137], v[76:77], v[148:149] op_sel_hi:[1,0]
	v_pk_fma_f32 v[110:111], v[118:119], v[142:143], v[72:73]
	v_pk_mul_f32 v[72:73], v[66:67], s[86:87] op_sel_hi:[1,0]
	v_pk_mul_f32 v[76:77], v[68:69], v[154:155] op_sel_hi:[1,0]
	v_exp_f32_e32 v72, v72
	v_exp_f32_e32 v73, v73
	v_mov_b32_dpp v70, v76 row_shr:1 row_mask:0xf bank_mask:0xf bound_ctrl:1
	v_mov_b32_dpp v71, v77 row_shr:1 row_mask:0xf bank_mask:0xf bound_ctrl:1
	v_pk_mul_f32 v[88:89], v[88:89], v[148:149] op_sel_hi:[1,0]
	v_pk_add_f32 v[72:73], v[72:73], 1.0 op_sel_hi:[1,0]
	v_mov_b32_dpp v68, v140 row_shr:1 row_mask:0xf bank_mask:0xf bound_ctrl:1
	v_rcp_f32_e32 v72, v72
	v_rcp_f32_e32 v73, v73
	v_mov_b32_dpp v69, v141 row_shr:1 row_mask:0xf bank_mask:0xf bound_ctrl:1
	v_pk_fma_f32 v[70:71], v[124:125], v[70:71], v[132:133]
	v_pk_mul_f32 v[84:85], v[84:85], v[156:157] op_sel_hi:[1,0]
	v_pk_fma_f32 v[70:71], v[128:129], v[68:69], v[70:71]
	v_pk_fma_f32 v[64:65], v[104:105], v[64:65], v[120:121]
; __device__ __forceinline__ unsigned cvt_pk_bf16(float lo, float hi) { unsigned r; asm volatile("v_cvt_pk_bf16_f32 %0, %1, %2" : "=v"(r) : "v"(lo), "v"(hi)); return r; }
;     __device__ __forceinline__ void operator()(const f32x4 (&acc)[2][2][4][2], const Unit& u, int wr, int wc, int fr, int fq) const {
;     ...
;                 f32x4 cg[4], cv[4];
;                 cg[0] = gb + g0 * G2s + g1 * G3s + g2 * G[0]; cv[0] = vb + v0 * V2s + v1 * V3s + v2 * V[0];
;                 cg[1] = gb + g0 * G3s + g1 * G[0] + g2 * G[1]; cv[1] = vb + v0 * V3s + v1 * V[0] + v2 * V[1];
;                 cg[2] = gb + g0 * G[0] + g1 * G[1] + g2 * G[2]; cv[2] = vb + v0 * V[0] + v1 * V[1] + v2 * V[2];
;                 cg[3] = gb + g0 * G[1] + g1 * G[2] + g2 * G[3]; cv[3] = vb + v0 * V[1] + v1 * V[2] + v2 * V[3];
; #pragma unroll
;                 for (int m = 0; m < 4; ++m) {
;                     const f32x2 a01 = silu_mul_pk((f32x2){cg[m][0], cg[m][1]}, (f32x2){cv[m][0], cv[m][1]}), a23 = silu_mul_pk((f32x2){cg[m][2], cg[m][3]}, (f32x2){cv[m][2], cv[m][3]});
;                     u32x2 w; w.x = cvt_pk_bf16(a01.x, a01.y); w.y = cvt_pk_bf16(a23.x, a23.y);
;                     if (n == 0) keep[ai][m] = w;
;                     else if (m >= 2 || fr != 0) { u32x4 o; o.x = keep[ai][m].x; o.y = keep[ai][m].y; o.z = w.x; o.w = w.y;
;                         *(u32x4*)(ACT + (size_t)(rbase + ai * HALF + m) * DFF + u.pn * HALF + wc * 32 + 8 * fq) = o; }
;                 }
;                 if (fr == 0) { *(f32x4*)(rawp) = G[0]; *(f32x4*)(rawp + HALF) = V[0]; *(f32x4*)(rawp + NUP) = G[1]; *(f32x4*)(rawp + NUP + HALF) = V[1]; }
;                 if (fr == 15) { *(f32x4*)(rawp + 2 * (size_t)NUP) = G[2]; *(f32x4*)(rawp + 2 * (size_t)NUP + HALF) = V[2]; *(f32x4*)(rawp + 3 * (size_t)NUP) = G[3]; *(f32x4*)(rawp + 3 * (size_t)NUP + HALF) = V[3]; }
	v_pk_fma_f32 v[170:171], v[104:105], v[92:93], v[120:121]
	v_pk_fma_f32 v[104:105], v[104:105], v[88:89], v[120:121]
	v_pk_fma_f32 v[74:75], v[114:115], v[94:95], v[74:75]
	v_pk_fma_f32 v[70:71], v[116:117], v[84:85], v[70:71]
	v_pk_fma_f32 v[64:65], v[108:109], v[92:93], v[64:65]
	v_pk_fma_f32 v[170:171], v[108:109], v[88:89], v[170:171]
	v_pk_fma_f32 v[104:105], v[108:109], v[144:145], v[104:105]
	v_pk_mul_f32 v[66:67], v[66:67], v[72:73]
	v_pk_fma_f32 v[64:65], v[112:113], v[88:89], v[64:65]
	v_pk_fma_f32 v[170:171], v[112:113], v[144:145], v[170:171]
	v_pk_fma_f32 v[104:105], v[112:113], v[80:81], v[104:105]
	v_pk_mul_f32 v[112:113], v[74:75], s[86:87] op_sel_hi:[1,0]
	v_pk_mul_f32 v[66:67], v[70:71], v[66:67]
	v_exp_f32_e32 v112, v112
	v_exp_f32_e32 v113, v113
	v_cvt_pk_bf16_f32 v72, v66, v67
	v_pk_mul_f32 v[66:67], v[64:65], s[86:87] op_sel_hi:[1,0]
	v_pk_fma_f32 v[68:69], v[124:125], v[68:69], v[132:133]
	v_exp_f32_e32 v66, v66
	v_exp_f32_e32 v67, v67
	v_pk_add_f32 v[112:113], v[112:113], 1.0 op_sel_hi:[1,0]
	v_pk_fma_f32 v[68:69], v[128:129], v[84:85], v[68:69]
	v_rcp_f32_e32 v112, v112
	v_rcp_f32_e32 v113, v113
	v_pk_add_f32 v[66:67], v[66:67], 1.0 op_sel_hi:[1,0]
	v_pk_fma_f32 v[68:69], v[116:117], v[136:137], v[68:69]
	v_rcp_f32_e32 v66, v66
	v_rcp_f32_e32 v67, v67
	v_pk_mul_f32 v[70:71], v[74:75], v[112:113]
	v_pk_mul_f32 v[74:75], v[168:169], s[86:87] op_sel_hi:[1,0]
	v_pk_fma_f32 v[166:167], v[118:119], v[86:87], v[166:167]
	v_exp_f32_e32 v74, v74
	v_exp_f32_e32 v75, v75
	v_pk_mul_f32 v[64:65], v[64:65], v[66:67]
	v_pk_mul_f32 v[70:71], v[166:167], v[70:71]
	v_pk_mul_f32 v[64:65], v[68:69], v[64:65]
	v_pk_mul_f32 v[68:69], v[218:219], s[86:87] op_sel_hi:[1,0]
	v_pk_add_f32 v[74:75], v[74:75], 1.0 op_sel_hi:[1,0]
	v_exp_f32_e32 v68, v68
	v_exp_f32_e32 v69, v69
	v_rcp_f32_e32 v74, v74
	v_rcp_f32_e32 v75, v75
	v_cvt_pk_bf16_f32 v73, v70, v71
	v_pk_add_f32 v[68:69], v[68:69], 1.0 op_sel_hi:[1,0]
	v_cvt_pk_bf16_f32 v70, v64, v65
	v_pk_mul_f32 v[66:67], v[168:169], v[74:75]
	v_rcp_f32_e32 v68, v68
	v_rcp_f32_e32 v69, v69
	v_pk_mul_f32 v[64:65], v[170:171], s[86:87] op_sel_hi:[1,0]
	v_pk_mul_f32 v[66:67], v[164:165], v[66:67]
	v_exp_f32_e32 v64, v64
	v_exp_f32_e32 v65, v65
	v_cvt_pk_bf16_f32 v71, v66, v67
	v_pk_mul_f32 v[66:67], v[218:219], v[68:69]
	v_pk_mul_f32 v[68:69], v[104:105], s[86:87] op_sel_hi:[1,0]
	v_pk_mul_f32 v[74:75], v[106:107], s[86:87] op_sel_hi:[1,0]
	v_exp_f32_e32 v68, v68
	v_exp_f32_e32 v69, v69
	v_exp_f32_e32 v74, v74
	v_exp_f32_e32 v75, v75
	v_pk_add_f32 v[64:65], v[64:65], 1.0 op_sel_hi:[1,0]
	s_add_i32 s36, s41, 2
	v_rcp_f32_e32 v64, v64
	v_rcp_f32_e32 v65, v65
	v_pk_add_f32 v[68:69], v[68:69], 1.0 op_sel_hi:[1,0]
	v_pk_add_f32 v[74:75], v[74:75], 1.0 op_sel_hi:[1,0]
	s_mul_hi_i32 s41, s36, 0x2c000
	s_mul_i32 s36, s36, 0x2c000
	v_pk_fma_f32 v[232:233], v[124:125], v[84:85], v[132:133]
	v_rcp_f32_e32 v68, v68
	v_rcp_f32_e32 v69, v69
	v_rcp_f32_e32 v74, v74
	v_rcp_f32_e32 v75, v75
	s_add_u32 s36, s5, s36
	v_pk_fma_f32 v[232:233], v[128:129], v[136:137], v[232:233]
	s_addc_u32 s41, s87, s41
	v_pk_fma_f32 v[232:233], v[116:117], v[76:77], v[232:233]
	v_pk_fma_f32 v[108:109], v[124:125], v[136:137], v[132:133]
	v_pk_mul_f32 v[64:65], v[170:171], v[64:65]
	s_add_u32 s42, s36, s56
	v_pk_fma_f32 v[108:109], v[128:129], v[76:77], v[108:109]
	v_pk_mul_f32 v[64:65], v[232:233], v[64:65]
	v_pk_mul_f32 v[66:67], v[234:235], v[66:67]
	s_addc_u32 s43, s41, s57
	v_pk_fma_f32 v[108:109], v[116:117], v[140:141], v[108:109]
	v_cvt_pk_bf16_f32 v64, v64, v65
	v_cvt_pk_bf16_f32 v65, v66, v67
	v_pk_mul_f32 v[66:67], v[104:105], v[68:69]
	v_pk_mul_f32 v[68:69], v[106:107], v[74:75]
	v_mov_b32_e32 v158, v156
	v_mov_b32_e32 v159, v156
	v_mov_b32_e32 v150, v148
	v_mov_b32_e32 v151, v148
	v_mov_b32_e32 v160, v154
	v_mov_b32_e32 v161, v154
	v_mov_b32_e32 v162, v152
	v_mov_b32_e32 v163, v152
	v_lshl_add_u64 v[118:119], v[180:181], 2, s[42:43]
	v_cmp_lt_i32_e32 vcc, 14, v227
	s_mov_b64 s[48:49], 0
	v_pk_mul_f32 v[66:67], v[108:109], v[66:67]
	v_pk_mul_f32 v[74:75], v[110:111], v[68:69]
	v_cvt_pk_bf16_f32 v68, v66, v67
	s_nop 0
	v_cvt_pk_bf16_f32 v69, v74, v75
	s_and_saveexec_b64 s[42:43], vcc
	s_xor_b64 s[42:43], exec, s[42:43]
	s_cbranch_execz .LBB0_981
	v_add_co_u32_e32 v66, vcc, 0x16000, v118
	s_mov_b64 s[48:49], exec
	s_nop 0
	v_addc_co_u32_e32 v67, vcc, 0, v119, vcc
	global_store_dwordx4 v[66:67], v[144:147], off nt
.LBB0_981:
	s_or_saveexec_b64 s[42:43], s[42:43]
	v_mov_b64_e32 v[74:75], 0x16200
	v_mov_b64_e32 v[66:67], 0x21000
	v_mov_b64_e32 v[104:105], 0x21200
	s_xor_b64 exec, exec, s[42:43]
	s_cbranch_execz .LBB0_985
	v_cmp_eq_u32_e32 vcc, 0, v227
	s_mov_b64 s[56:57], s[48:49]
	s_and_saveexec_b64 s[58:59], vcc
	s_cbranch_execz .LBB0_984
	s_or_b64 s[56:57], s[48:49], exec
	global_store_dwordx4 v[118:119], v[92:95], off nt

;     __device__ __forceinline__ void operator()(const f32x4 (&acc)[2][2][4][2], const Unit& u, int wr, int wc, int fr, int fq) const {
;     ...
;         for (int n = 0; n < 2; ++n) {
;             const int ci = wc * 32 + 8 * fq + 4 * n, cgc = u.pn * HALF + ci;
;             const f32x4 g0 = *(const f32x4*)(cw + cgc), g1 = *(const f32x4*)(cw + NUP + cgc), g2 = *(const f32x4*)(cw + 2 * NUP + cgc), gb = *(const f32x4*)(cb + cgc);
;             const f32x4 v0 = *(const f32x4*)(cw + DFF + cgc), v1 = *(const f32x4*)(cw + NUP + DFF + cgc), v2 = *(const f32x4*)(cw + 2 * NUP + DFF + cgc), vb = *(const f32x4*)(cb + DFF + cgc);
; #pragma unroll
;             for (int ai = 0; ai < 2; ++ai) {
;                 float* rawp = RAW + ((size_t)(u.pm * 4 + ai * 2 + wr) * 4) * NUP + u.pn * BM + ci;
;                 f32x4 G[4], V[4];
; #pragma unroll
;                 for (int m = 0; m < 4; ++m) { G[m] = acc[ai][0][m][n] * rs[ai][m]; V[m] = acc[ai][1][m][n] * rs[ai][m]; }
;                 f32x4 G3s, G2s, V3s, V2s;
; #pragma unroll
;                 for (int e = 0; e < 4; ++e) { G3s[e] = dppz<0x111>(G[3][e]); G2s[e] = dppz<0x111>(G[2][e]); V3s[e] = dppz<0x111>(V[3][e]); V2s[e] = dppz<0x111>(V[2][e]); }
;                 f32x4 cg[4], cv[4];
;                 cg[0] = gb + g0 * G2s + g1 * G3s + g2 * G[0]; cv[0] = vb + v0 * V2s + v1 * V3s + v2 * V[0];
;                 cg[1] = gb + g0 * G3s + g1 * G[0] + g2 * G[1]; cv[1] = vb + v0 * V3s + v1 * V[0] + v2 * V[1];
;                 cg[2] = gb + g0 * G[0] + g1 * G[1] + g2 * G[2]; cv[2] = vb + v0 * V[0] + v1 * V[1] + v2 * V[2];
;                 cg[3] = gb + g0 * G[1] + g1 * G[2] + g2 * G[3]; cv[3] = vb + v0 * V[1] + v1 * V[2] + v2 * V[3];
; #pragma unroll
;                 for (int m = 0; m < 4; ++m) {
;                     const f32x2 a01 = silu_mul_pk((f32x2){cg[m][0], cg[m][1]}, (f32x2){cv[m][0], cv[m][1]}), a23 = silu_mul_pk((f32x2){cg[m][2], cg[m][3]}, (f32x2){cv[m][2], cv[m][3]});
;                     u32x2 w; w.x = cvt_pk_bf16(a01.x, a01.y); w.y = cvt_pk_bf16(a23.x, a23.y);
;                     if (n == 0) keep[ai][m] = w;
;                     else if (m >= 2 || fr != 0) { u32x4 o; o.x = keep[ai][m].x; o.y = keep[ai][m].y; o.z = w.x; o.w = w.y;
;                         *(u32x4*)(ACT + (size_t)(rbase + ai * HALF + m) * DFF + u.pn * HALF + wc * 32 + 8 * fq) = o; }
.LBB0_985:
	s_or_b64 exec, exec, s[42:43]
	s_and_saveexec_b64 s[42:43], s[48:49]
	s_cbranch_execz .LBB0_987
	v_lshl_add_u64 v[74:75], v[118:119], 0, v[74:75]
	v_lshl_add_u64 v[66:67], v[118:119], 0, v[66:67]
	global_store_dwordx4 v[74:75], v[76:79], off nt
	global_store_dwordx4 v[66:67], v[80:83], off nt
	v_lshl_add_u64 v[66:67], v[118:119], 0, v[104:105]
	global_store_dwordx4 v[66:67], v[140:143], off nt
.LBB0_987:
	s_or_b64 exec, exec, s[42:43]
	v_add_u32_e32 v66, s54, v230
	v_ashrrev_i32_e32 v67, 31, v66
	v_lshlrev_b64 v[66:67], 2, v[66:67]
	v_lshl_add_u64 v[74:75], s[16:17], 0, v[66:67]
	global_load_dwordx4 v[84:87], v[206:207], off offset:16
	global_load_dwordx4 v[88:91], v[74:75], off
	v_lshl_add_u64 v[74:75], s[18:19], 0, v[66:67]
	global_load_dwordx4 v[80:83], v[74:75], off
	global_load_dwordx4 v[110:113], v[208:209], off offset:16
	v_lshl_add_u64 v[74:75], s[28:29], 0, v[66:67]
	global_load_dwordx4 v[92:95], v[74:75], off
	v_lshl_add_u64 v[74:75], s[44:45], 0, v[66:67]
	global_load_dwordx4 v[106:109], v[74:75], off
	v_lshl_add_u64 v[74:75], s[46:47], 0, v[66:67]
	v_lshl_add_u64 v[66:67], s[66:67], 0, v[66:67]
	global_load_dwordx4 v[114:117], v[66:67], off
	global_load_dwordx4 v[76:79], v[74:75], off
	v_pk_mul_f32 v[56:57], v[56:57], v[202:203]
	v_pk_mul_f32 v[48:49], v[48:49], v[200:201]
	v_pk_mul_f32 v[60:61], v[60:61], v[204:205]
	v_mov_b32_dpp v104, v56 row_shr:1 row_mask:0xf bank_mask:0xf bound_ctrl:1
	v_mov_b32_dpp v105, v57 row_shr:1 row_mask:0xf bank_mask:0xf bound_ctrl:1
	v_mov_b32_dpp v74, v48 row_shr:1 row_mask:0xf bank_mask:0xf bound_ctrl:1
	v_mov_b32_dpp v75, v49 row_shr:1 row_mask:0xf bank_mask:0xf bound_ctrl:1
	v_pk_mul_f32 v[58:59], v[58:59], v[214:215]
	v_pk_mul_f32 v[44:45], v[44:45], v[202:203]
	v_pk_mul_f32 v[50:51], v[50:51], v[216:217]
	v_pk_mul_f32 v[40:41], v[40:41], v[200:201]
	v_mov_b32_dpp v124, v44 row_shr:1 row_mask:0xf bank_mask:0xf bound_ctrl:1
	v_mov_b32_dpp v125, v45 row_shr:1 row_mask:0xf bank_mask:0xf bound_ctrl:1
	v_mov_b32_dpp v126, v58 row_shr:1 row_mask:0xf bank_mask:0xf bound_ctrl:1
	v_mov_b32_dpp v127, v59 row_shr:1 row_mask:0xf bank_mask:0xf bound_ctrl:1
	v_mov_b32_dpp v66, v40 row_shr:1 row_mask:0xf bank_mask:0xf bound_ctrl:1
	v_mov_b32_dpp v67, v41 row_shr:1 row_mask:0xf bank_mask:0xf bound_ctrl:1
	v_mov_b32_dpp v122, v50 row_shr:1 row_mask:0xf bank_mask:0xf bound_ctrl:1
	v_mov_b32_dpp v123, v51 row_shr:1 row_mask:0xf bank_mask:0xf bound_ctrl:1
	v_pk_mul_f32 v[62:63], v[62:63], v[212:213]
	v_pk_mul_f32 v[52:53], v[52:53], v[204:205]
	v_pk_mul_f32 v[46:47], v[46:47], v[214:215]
	v_pk_mul_f32 v[42:43], v[42:43], v[216:217]
	v_pk_mul_f32 v[54:55], v[54:55], v[212:213]
	v_mov_b32_dpp v128, v46 row_shr:1 row_mask:0xf bank_mask:0xf bound_ctrl:1
	v_mov_b32_dpp v129, v47 row_shr:1 row_mask:0xf bank_mask:0xf bound_ctrl:1
	v_mov_b32_dpp v120, v42 row_shr:1 row_mask:0xf bank_mask:0xf bound_ctrl:1
	v_mov_b32_dpp v121, v43 row_shr:1 row_mask:0xf bank_mask:0xf bound_ctrl:1
	s_ashr_i32 s55, s54, 31
	s_waitcnt vmcnt(4)
	v_pk_fma_f32 v[104:105], v[84:85], v[104:105], v[110:111]
	s_nop 0
	v_pk_fma_f32 v[104:105], v[88:89], v[74:75], v[104:105]
	v_pk_fma_f32 v[126:127], v[86:87], v[126:127], v[112:113]
	v_pk_fma_f32 v[104:105], v[60:61], v[80:81], v[104:105]
	v_pk_fma_f32 v[126:127], v[90:91], v[122:123], v[126:127]
	v_pk_mul_f32 v[130:131], v[104:105], s[86:87] op_sel_hi:[1,0]
	v_pk_fma_f32 v[126:127], v[62:63], v[82:83], v[126:127]
	v_exp_f32_e32 v130, v130
	v_exp_f32_e32 v131, v131
	s_waitcnt vmcnt(1)
	v_pk_fma_f32 v[124:125], v[92:93], v[124:125], v[114:115]
	v_pk_fma_f32 v[128:129], v[94:95], v[128:129], v[116:117]
	v_pk_fma_f32 v[124:125], v[106:107], v[66:67], v[124:125]
	v_pk_add_f32 v[130:131], v[130:131], 1.0 op_sel_hi:[1,0]
	s_waitcnt vmcnt(0)
	v_pk_fma_f32 v[124:125], v[52:53], v[76:77], v[124:125]
	v_rcp_f32_e32 v130, v130
	v_rcp_f32_e32 v131, v131
	v_pk_fma_f32 v[128:129], v[108:109], v[120:121], v[128:129]
	v_pk_mul_f32 v[104:105], v[104:105], v[130:131]
	s_nop 0
	v_pk_mul_f32 v[104:105], v[124:125], v[104:105]
	v_pk_mul_f32 v[124:125], v[126:127], s[86:87] op_sel_hi:[1,0]
	v_pk_fma_f32 v[128:129], v[54:55], v[78:79], v[128:129]
	v_exp_f32_e32 v124, v124
	v_exp_f32_e32 v125, v125
	v_cvt_pk_bf16_f32 v104, v104, v105
	s_nop 0
	v_pk_add_f32 v[124:125], v[124:125], 1.0 op_sel_hi:[1,0]
	s_nop 0
	v_rcp_f32_e32 v124, v124
	v_rcp_f32_e32 v125, v125
	s_nop 0
	v_pk_mul_f32 v[124:125], v[126:127], v[124:125]
	s_nop 0
	v_pk_mul_f32 v[124:125], v[128:129], v[124:125]
	s_nop 0
	v_cvt_pk_bf16_f32 v105, v124, v125
	s_and_saveexec_b64 s[42:43], s[8:9]
	s_cbranch_execz .LBB0_989
	v_mov_b64_e32 v[124:125], s[34:35]
	v_mad_i64_i32 v[124:125], s[48:49], v186, s26, v[124:125]
	v_lshl_add_u64 v[124:125], s[54:55], 1, v[124:125]
	s_lshl_b32 s36, s69, 1
	v_lshl_add_u64 v[124:125], v[124:125], 0, s[36:37]
	v_lshl_add_u64 v[124:125], v[178:179], 1, v[124:125]
	global_store_dwordx4 v[124:125], v[102:105], off nt
; __device__ __forceinline__ unsigned cvt_pk_bf16(float lo, float hi) { unsigned r; asm volatile("v_cvt_pk_bf16_f32 %0, %1, %2" : "=v"(r) : "v"(lo), "v"(hi)); return r; }
;     __device__ __forceinline__ void operator()(const f32x4 (&acc)[2][2][4][2], const Unit& u, int wr, int wc, int fr, int fq) const {
;     ...
;                 f32x4 cg[4], cv[4];
;                 cg[0] = gb + g0 * G2s + g1 * G3s + g2 * G[0]; cv[0] = vb + v0 * V2s + v1 * V3s + v2 * V[0];
;                 cg[1] = gb + g0 * G3s + g1 * G[0] + g2 * G[1]; cv[1] = vb + v0 * V3s + v1 * V[0] + v2 * V[1];
;                 cg[2] = gb + g0 * G[0] + g1 * G[1] + g2 * G[2]; cv[2] = vb + v0 * V[0] + v1 * V[1] + v2 * V[2];
;                 cg[3] = gb + g0 * G[1] + g1 * G[2] + g2 * G[3]; cv[3] = vb + v0 * V[1] + v1 * V[2] + v2 * V[3];
; #pragma unroll
;                 for (int m = 0; m < 4; ++m) {
;                     const f32x2 a01 = silu_mul_pk((f32x2){cg[m][0], cg[m][1]}, (f32x2){cv[m][0], cv[m][1]}), a23 = silu_mul_pk((f32x2){cg[m][2], cg[m][3]}, (f32x2){cv[m][2], cv[m][3]});
;                     u32x2 w; w.x = cvt_pk_bf16(a01.x, a01.y); w.y = cvt_pk_bf16(a23.x, a23.y);
;                     if (n == 0) keep[ai][m] = w;
;                     else if (m >= 2 || fr != 0) { u32x4 o; o.x = keep[ai][m].x; o.y = keep[ai][m].y; o.z = w.x; o.w = w.y;
;                         *(u32x4*)(ACT + (size_t)(rbase + ai * HALF + m) * DFF + u.pn * HALF + wc * 32 + 8 * fq) = o; }
;                 }
;                 if (fr == 0) { *(f32x4*)(rawp) = G[0]; *(f32x4*)(rawp + HALF) = V[0]; *(f32x4*)(rawp + NUP) = G[1]; *(f32x4*)(rawp + NUP + HALF) = V[1]; }
;                 if (fr == 15) { *(f32x4*)(rawp + 2 * (size_t)NUP) = G[2]; *(f32x4*)(rawp + 2 * (size_t)NUP + HALF) = V[2]; *(f32x4*)(rawp + 3 * (size_t)NUP) = G[3]; *(f32x4*)(rawp + 3 * (size_t)NUP + HALF) = V[3]; }
.LBB0_989:
	s_or_b64 exec, exec, s[42:43]
	v_pk_fma_f32 v[74:75], v[84:85], v[74:75], v[110:111]
	v_pk_mul_f32 v[36:37], v[36:37], v[188:189]
	v_pk_fma_f32 v[102:103], v[86:87], v[122:123], v[112:113]
	v_pk_fma_f32 v[74:75], v[60:61], v[88:89], v[74:75]
	v_pk_mul_f32 v[38:39], v[38:39], v[190:191]
	v_pk_fma_f32 v[102:103], v[62:63], v[90:91], v[102:103]
	v_pk_fma_f32 v[74:75], v[36:37], v[80:81], v[74:75]
	v_pk_fma_f32 v[102:103], v[38:39], v[82:83], v[102:103]
	v_pk_fma_f32 v[104:105], v[94:95], v[120:121], v[116:117]
	v_pk_mul_f32 v[120:121], v[74:75], s[86:87] op_sel_hi:[1,0]
	v_pk_mul_f32 v[122:123], v[102:103], s[86:87] op_sel_hi:[1,0]
	v_exp_f32_e32 v120, v120
	v_exp_f32_e32 v121, v121
	v_exp_f32_e32 v122, v122
	v_exp_f32_e32 v123, v123
	v_pk_fma_f32 v[66:67], v[92:93], v[66:67], v[114:115]
	v_pk_add_f32 v[120:121], v[120:121], 1.0 op_sel_hi:[1,0]
	v_pk_mul_f32 v[32:33], v[32:33], v[188:189]
	v_rcp_f32_e32 v120, v120
	v_rcp_f32_e32 v121, v121
	v_pk_add_f32 v[122:123], v[122:123], 1.0 op_sel_hi:[1,0]
	v_pk_fma_f32 v[66:67], v[52:53], v[106:107], v[66:67]
	v_rcp_f32_e32 v122, v122
	v_rcp_f32_e32 v123, v123
	v_pk_mul_f32 v[34:35], v[34:35], v[190:191]
	v_pk_fma_f32 v[104:105], v[54:55], v[108:109], v[104:105]
	v_pk_fma_f32 v[66:67], v[32:33], v[76:77], v[66:67]
	v_pk_mul_f32 v[74:75], v[74:75], v[120:121]
	v_pk_fma_f32 v[104:105], v[34:35], v[78:79], v[104:105]
	v_pk_mul_f32 v[66:67], v[66:67], v[74:75]
	v_pk_mul_f32 v[74:75], v[102:103], v[122:123]
	v_cvt_pk_bf16_f32 v102, v66, v67
	s_nop 0
	v_pk_mul_f32 v[74:75], v[104:105], v[74:75]
	s_nop 0
	v_cvt_pk_bf16_f32 v103, v74, v75
	s_and_saveexec_b64 s[42:43], s[8:9]
	s_cbranch_execz .LBB0_991
	v_or_b32_e32 v74, 1, v186
	v_mov_b64_e32 v[66:67], s[34:35]
	v_mad_i64_i32 v[66:67], s[48:49], v74, s26, v[66:67]
	v_lshl_add_u64 v[66:67], s[54:55], 1, v[66:67]
	s_lshl_b32 s36, s69, 1
	v_lshl_add_u64 v[66:67], v[66:67], 0, s[36:37]
	v_lshl_add_u64 v[66:67], v[178:179], 1, v[66:67]
	global_store_dwordx4 v[66:67], v[100:103], off nt
.LBB0_991:
	s_or_b64 exec, exec, s[42:43]
	v_pk_fma_f32 v[74:75], v[60:61], v[84:85], v[110:111]
	v_pk_fma_f32 v[66:67], v[62:63], v[86:87], v[112:113]
	v_pk_fma_f32 v[74:75], v[36:37], v[88:89], v[74:75]
	v_pk_fma_f32 v[102:103], v[52:53], v[92:93], v[114:115]
	v_pk_fma_f32 v[74:75], v[56:57], v[80:81], v[74:75]
	v_pk_fma_f32 v[66:67], v[38:39], v[90:91], v[66:67]
	v_pk_mul_f32 v[126:127], v[74:75], s[86:87] op_sel_hi:[1,0]
	v_pk_fma_f32 v[102:103], v[32:33], v[106:107], v[102:103]
	v_exp_f32_e32 v126, v126
	v_exp_f32_e32 v127, v127
	v_pk_fma_f32 v[66:67], v[58:59], v[82:83], v[66:67]
	v_pk_fma_f32 v[102:103], v[44:45], v[76:77], v[102:103]
	v_pk_fma_f32 v[100:101], v[54:55], v[94:95], v[116:117]
	v_pk_add_f32 v[126:127], v[126:127], 1.0 op_sel_hi:[1,0]
	v_pk_fma_f32 v[100:101], v[34:35], v[108:109], v[100:101]
	v_rcp_f32_e32 v126, v126
	v_rcp_f32_e32 v127, v127
	v_pk_fma_f32 v[100:101], v[46:47], v[78:79], v[100:101]
	s_lshl_b64 s[56:57], s[54:55], 1
	v_pk_fma_f32 v[120:121], v[36:37], v[84:85], v[110:111]
	v_pk_mul_f32 v[74:75], v[74:75], v[126:127]
	s_lshl_b32 s36, s69, 1
	v_pk_mul_f32 v[74:75], v[102:103], v[74:75]
	v_pk_mul_f32 v[102:103], v[66:67], s[86:87] op_sel_hi:[1,0]
	v_pk_fma_f32 v[104:105], v[38:39], v[86:87], v[112:113]
	v_exp_f32_e32 v102, v102
	v_exp_f32_e32 v103, v103
	v_pk_fma_f32 v[120:121], v[56:57], v[88:89], v[120:121]
	v_pk_fma_f32 v[104:105], v[58:59], v[90:91], v[104:105]
	v_pk_fma_f32 v[120:121], v[48:49], v[80:81], v[120:121]
	v_pk_add_f32 v[102:103], v[102:103], 1.0 op_sel_hi:[1,0]
	v_pk_fma_f32 v[104:105], v[50:51], v[82:83], v[104:105]
	v_rcp_f32_e32 v102, v102
	v_rcp_f32_e32 v103, v103
	v_pk_fma_f32 v[124:125], v[32:33], v[92:93], v[114:115]
	v_pk_fma_f32 v[122:123], v[34:35], v[94:95], v[116:117]
	v_pk_fma_f32 v[124:125], v[44:45], v[106:107], v[124:125]
	v_pk_mul_f32 v[66:67], v[66:67], v[102:103]
	v_lshlrev_b64 v[102:103], 1, v[178:179]
	v_pk_mul_f32 v[66:67], v[100:101], v[66:67]
	v_cvt_pk_bf16_f32 v100, v74, v75
	v_or_b32_e32 v74, 2, v186
	v_cvt_pk_bf16_f32 v101, v66, v67
	v_mov_b64_e32 v[66:67], s[34:35]
	v_mad_i64_i32 v[74:75], s[42:43], v74, s26, v[66:67]
	v_lshl_add_u64 v[74:75], v[74:75], 0, s[56:57]
	v_lshl_add_u64 v[74:75], v[74:75], 0, s[36:37]
	v_lshl_add_u64 v[74:75], v[74:75], 0, v[102:103]
	global_store_dwordx4 v[74:75], v[98:101], off nt
	v_pk_mul_f32 v[74:75], v[120:121], s[86:87] op_sel_hi:[1,0]
	v_pk_fma_f32 v[122:123], v[46:47], v[108:109], v[122:123]
	v_exp_f32_e32 v74, v74
	v_exp_f32_e32 v75, v75
	v_pk_mul_f32 v[98:99], v[104:105], s[86:87] op_sel_hi:[1,0]
	v_pk_fma_f32 v[124:125], v[40:41], v[76:77], v[124:125]
	v_exp_f32_e32 v98, v98
	v_exp_f32_e32 v99, v99
	v_pk_add_f32 v[74:75], v[74:75], 1.0 op_sel_hi:[1,0]
	v_pk_fma_f32 v[122:123], v[42:43], v[78:79], v[122:123]
	v_rcp_f32_e32 v74, v74
	v_rcp_f32_e32 v75, v75
	v_pk_add_f32 v[98:99], v[98:99], 1.0 op_sel_hi:[1,0]
	v_cmp_lt_i32_e32 vcc, 14, v227
	v_rcp_f32_e32 v98, v98
	v_rcp_f32_e32 v99, v99
	v_pk_mul_f32 v[74:75], v[120:121], v[74:75]
	s_mov_b64 s[48:49], 0
	v_pk_mul_f32 v[74:75], v[124:125], v[74:75]
	v_pk_mul_f32 v[98:99], v[104:105], v[98:99]
	s_nop 0
	v_pk_mul_f32 v[100:101], v[122:123], v[98:99]
	v_cvt_pk_bf16_f32 v98, v74, v75
	v_or_b32_e32 v74, 3, v186
	v_mad_i64_i32 v[66:67], s[42:43], v74, s26, v[66:67]
	v_lshl_add_u64 v[66:67], v[66:67], 0, s[56:57]
	v_lshl_add_u64 v[66:67], v[66:67], 0, s[36:37]
	v_lshl_add_u64 v[66:67], v[66:67], 0, v[102:103]
	v_cvt_pk_bf16_f32 v99, v100, v101
	global_store_dwordx4 v[66:67], v[96:99], off nt
	v_lshl_add_u64 v[66:67], v[210:211], 0, 16
	s_and_saveexec_b64 s[42:43], vcc
	s_xor_b64 s[42:43], exec, s[42:43]
	s_cbranch_execz .LBB0_993
	v_add_co_u32_e32 v32, vcc, 0x16000, v66
	s_mov_b64 s[48:49], exec
	s_nop 0
	v_addc_co_u32_e32 v33, vcc, 0, v67, vcc
	global_store_dwordx4 v[32:33], v[56:59], off nt
.LBB0_993:
	s_or_saveexec_b64 s[42:43], s[42:43]
	s_nop 0
	v_mov_b64_e32 v[58:59], 0x16200
	v_mov_b64_e32 v[56:57], 0x21000
	v_mov_b64_e32 v[74:75], 0x21200
	s_xor_b64 exec, exec, s[42:43]
	s_cbranch_execz .LBB0_997
	v_cmp_eq_u32_e32 vcc, 0, v227
	s_mov_b64 s[58:59], s[48:49]
	s_and_saveexec_b64 s[60:61], vcc
	s_cbranch_execz .LBB0_996
	s_or_b64 s[58:59], s[48:49], exec
	global_store_dwordx4 v[66:67], v[60:63], off nt

; __device__ __forceinline__ unsigned cvt_pk_bf16(float lo, float hi) { unsigned r; asm volatile("v_cvt_pk_bf16_f32 %0, %1, %2" : "=v"(r) : "v"(lo), "v"(hi)); return r; }
;     __device__ __forceinline__ void operator()(const f32x4 (&acc)[2][2][4][2], const Unit& u, int wr, int wc, int fr, int fq) const {
;     ...
;                 f32x4 cg[4], cv[4];
;                 cg[0] = gb + g0 * G2s + g1 * G3s + g2 * G[0]; cv[0] = vb + v0 * V2s + v1 * V3s + v2 * V[0];
;                 cg[1] = gb + g0 * G3s + g1 * G[0] + g2 * G[1]; cv[1] = vb + v0 * V3s + v1 * V[0] + v2 * V[1];
;                 cg[2] = gb + g0 * G[0] + g1 * G[1] + g2 * G[2]; cv[2] = vb + v0 * V[0] + v1 * V[1] + v2 * V[2];
;                 cg[3] = gb + g0 * G[1] + g1 * G[2] + g2 * G[3]; cv[3] = vb + v0 * V[1] + v1 * V[2] + v2 * V[3];
; #pragma unroll
;                 for (int m = 0; m < 4; ++m) {
;                     const f32x2 a01 = silu_mul_pk((f32x2){cg[m][0], cg[m][1]}, (f32x2){cv[m][0], cv[m][1]}), a23 = silu_mul_pk((f32x2){cg[m][2], cg[m][3]}, (f32x2){cv[m][2], cv[m][3]});
;                     u32x2 w; w.x = cvt_pk_bf16(a01.x, a01.y); w.y = cvt_pk_bf16(a23.x, a23.y);
;                     if (n == 0) keep[ai][m] = w;
;                     else if (m >= 2 || fr != 0) { u32x4 o; o.x = keep[ai][m].x; o.y = keep[ai][m].y; o.z = w.x; o.w = w.y;
;                         *(u32x4*)(ACT + (size_t)(rbase + ai * HALF + m) * DFF + u.pn * HALF + wc * 32 + 8 * fq) = o; }
;                 }
;                 if (fr == 0) { *(f32x4*)(rawp) = G[0]; *(f32x4*)(rawp + HALF) = V[0]; *(f32x4*)(rawp + NUP) = G[1]; *(f32x4*)(rawp + NUP + HALF) = V[1]; }
;                 if (fr == 15) { *(f32x4*)(rawp + 2 * (size_t)NUP) = G[2]; *(f32x4*)(rawp + 2 * (size_t)NUP + HALF) = V[2]; *(f32x4*)(rawp + 3 * (size_t)NUP) = G[3]; *(f32x4*)(rawp + 3 * (size_t)NUP + HALF) = V[3]; }
.LBB0_997:
	s_or_b64 exec, exec, s[42:43]
	s_and_saveexec_b64 s[42:43], s[48:49]
	s_cbranch_execz .LBB0_999
	v_lshl_add_u64 v[32:33], v[210:211], 0, v[58:59]
	global_store_dwordx4 v[32:33], v[44:47], off offset:16 nt
	v_lshl_add_u64 v[32:33], v[210:211], 0, v[56:57]
	global_store_dwordx4 v[32:33], v[48:51], off offset:16 nt
	v_lshl_add_u64 v[32:33], v[210:211], 0, v[74:75]
	global_store_dwordx4 v[32:33], v[40:43], off offset:16 nt
.LBB0_999:
	s_or_b64 exec, exec, s[42:43]
	v_pk_mul_f32 v[24:25], v[24:25], v[154:155]
	v_pk_mul_f32 v[16:17], v[16:17], v[152:153]
	v_pk_mul_f32 v[28:29], v[28:29], v[156:157]
	v_mov_b32_dpp v40, v24 row_shr:1 row_mask:0xf bank_mask:0xf bound_ctrl:1
	v_mov_b32_dpp v41, v25 row_shr:1 row_mask:0xf bank_mask:0xf bound_ctrl:1
	v_mov_b32_dpp v34, v16 row_shr:1 row_mask:0xf bank_mask:0xf bound_ctrl:1
	v_mov_b32_dpp v35, v17 row_shr:1 row_mask:0xf bank_mask:0xf bound_ctrl:1
	v_pk_fma_f32 v[40:41], v[84:85], v[40:41], v[110:111]
	v_pk_mul_f32 v[26:27], v[26:27], v[160:161]
	v_pk_fma_f32 v[40:41], v[88:89], v[34:35], v[40:41]
	v_pk_mul_f32 v[12:13], v[12:13], v[154:155]
	v_pk_fma_f32 v[40:41], v[28:29], v[80:81], v[40:41]
	v_pk_mul_f32 v[18:19], v[18:19], v[162:163]
	v_pk_mul_f32 v[48:49], v[40:41], s[86:87] op_sel_hi:[1,0]
	v_pk_mul_f32 v[8:9], v[8:9], v[152:153]
	v_exp_f32_e32 v48, v48
	v_exp_f32_e32 v49, v49
	v_mov_b32_dpp v42, v12 row_shr:1 row_mask:0xf bank_mask:0xf bound_ctrl:1
	v_mov_b32_dpp v43, v13 row_shr:1 row_mask:0xf bank_mask:0xf bound_ctrl:1
	v_mov_b32_dpp v44, v26 row_shr:1 row_mask:0xf bank_mask:0xf bound_ctrl:1
	v_pk_add_f32 v[48:49], v[48:49], 1.0 op_sel_hi:[1,0]
	v_mov_b32_dpp v45, v27 row_shr:1 row_mask:0xf bank_mask:0xf bound_ctrl:1
	v_rcp_f32_e32 v48, v48
	v_rcp_f32_e32 v49, v49
	v_mov_b32_dpp v32, v8 row_shr:1 row_mask:0xf bank_mask:0xf bound_ctrl:1
	v_mov_b32_dpp v33, v9 row_shr:1 row_mask:0xf bank_mask:0xf bound_ctrl:1
	v_mov_b32_dpp v38, v18 row_shr:1 row_mask:0xf bank_mask:0xf bound_ctrl:1
	v_mov_b32_dpp v39, v19 row_shr:1 row_mask:0xf bank_mask:0xf bound_ctrl:1
	v_pk_fma_f32 v[44:45], v[86:87], v[44:45], v[112:113]
	v_pk_fma_f32 v[42:43], v[92:93], v[42:43], v[114:115]
	v_pk_mul_f32 v[30:31], v[30:31], v[158:159]
	v_pk_mul_f32 v[20:21], v[20:21], v[156:157]
	v_pk_fma_f32 v[44:45], v[90:91], v[38:39], v[44:45]
	v_pk_fma_f32 v[42:43], v[106:107], v[32:33], v[42:43]
	v_pk_fma_f32 v[44:45], v[30:31], v[82:83], v[44:45]
	v_pk_fma_f32 v[42:43], v[20:21], v[76:77], v[42:43]
	v_pk_mul_f32 v[40:41], v[40:41], v[48:49]
	v_pk_mul_f32 v[14:15], v[14:15], v[160:161]
	v_pk_mul_f32 v[40:41], v[42:43], v[40:41]
	v_pk_mul_f32 v[42:43], v[44:45], s[86:87] op_sel_hi:[1,0]
	v_pk_mul_f32 v[10:11], v[10:11], v[162:163]
	v_exp_f32_e32 v42, v42
	v_exp_f32_e32 v43, v43
	v_mov_b32_dpp v46, v14 row_shr:1 row_mask:0xf bank_mask:0xf bound_ctrl:1
	v_mov_b32_dpp v47, v15 row_shr:1 row_mask:0xf bank_mask:0xf bound_ctrl:1
	v_mov_b32_dpp v36, v10 row_shr:1 row_mask:0xf bank_mask:0xf bound_ctrl:1
	v_pk_add_f32 v[42:43], v[42:43], 1.0 op_sel_hi:[1,0]
	v_mov_b32_dpp v37, v11 row_shr:1 row_mask:0xf bank_mask:0xf bound_ctrl:1
	v_rcp_f32_e32 v42, v42
	v_rcp_f32_e32 v43, v43
	v_pk_fma_f32 v[46:47], v[94:95], v[46:47], v[116:117]
	v_pk_mul_f32 v[22:23], v[22:23], v[158:159]
	v_pk_fma_f32 v[46:47], v[108:109], v[36:37], v[46:47]
	v_pk_mul_f32 v[42:43], v[44:45], v[42:43]
	v_pk_fma_f32 v[46:47], v[22:23], v[78:79], v[46:47]
	v_cvt_pk_bf16_f32 v74, v40, v41
	s_nop 0
	v_pk_mul_f32 v[42:43], v[46:47], v[42:43]
	s_nop 0
	v_cvt_pk_bf16_f32 v75, v42, v43
	s_and_saveexec_b64 s[42:43], s[8:9]
	s_cbranch_execz .LBB0_1001
	v_add_u32_e32 v42, 0x80, v186
	v_mov_b64_e32 v[40:41], s[34:35]
	v_mad_i64_i32 v[40:41], s[48:49], v42, s26, v[40:41]
	v_lshl_add_u64 v[40:41], s[54:55], 1, v[40:41]
	v_lshl_add_u64 v[40:41], v[40:41], 0, s[36:37]
	v_lshl_add_u64 v[40:41], v[178:179], 1, v[40:41]
	global_store_dwordx4 v[40:41], v[72:75], off nt
; __device__ __forceinline__ unsigned cvt_pk_bf16(float lo, float hi) { unsigned r; asm volatile("v_cvt_pk_bf16_f32 %0, %1, %2" : "=v"(r) : "v"(lo), "v"(hi)); return r; }
;     __device__ __forceinline__ void operator()(const f32x4 (&acc)[2][2][4][2], const Unit& u, int wr, int wc, int fr, int fq) const {
;     ...
;                 f32x4 cg[4], cv[4];
;                 cg[0] = gb + g0 * G2s + g1 * G3s + g2 * G[0]; cv[0] = vb + v0 * V2s + v1 * V3s + v2 * V[0];
;                 cg[1] = gb + g0 * G3s + g1 * G[0] + g2 * G[1]; cv[1] = vb + v0 * V3s + v1 * V[0] + v2 * V[1];
;                 cg[2] = gb + g0 * G[0] + g1 * G[1] + g2 * G[2]; cv[2] = vb + v0 * V[0] + v1 * V[1] + v2 * V[2];
;                 cg[3] = gb + g0 * G[1] + g1 * G[2] + g2 * G[3]; cv[3] = vb + v0 * V[1] + v1 * V[2] + v2 * V[3];
; #pragma unroll
;                 for (int m = 0; m < 4; ++m) {
;                     const f32x2 a01 = silu_mul_pk((f32x2){cg[m][0], cg[m][1]}, (f32x2){cv[m][0], cv[m][1]}), a23 = silu_mul_pk((f32x2){cg[m][2], cg[m][3]}, (f32x2){cv[m][2], cv[m][3]});
;                     u32x2 w; w.x = cvt_pk_bf16(a01.x, a01.y); w.y = cvt_pk_bf16(a23.x, a23.y);
;                     if (n == 0) keep[ai][m] = w;
;                     else if (m >= 2 || fr != 0) { u32x4 o; o.x = keep[ai][m].x; o.y = keep[ai][m].y; o.z = w.x; o.w = w.y;
;                         *(u32x4*)(ACT + (size_t)(rbase + ai * HALF + m) * DFF + u.pn * HALF + wc * 32 + 8 * fq) = o; }
;                 }
;                 if (fr == 0) { *(f32x4*)(rawp) = G[0]; *(f32x4*)(rawp + HALF) = V[0]; *(f32x4*)(rawp + NUP) = G[1]; *(f32x4*)(rawp + NUP + HALF) = V[1]; }
;                 if (fr == 15) { *(f32x4*)(rawp + 2 * (size_t)NUP) = G[2]; *(f32x4*)(rawp + 2 * (size_t)NUP + HALF) = V[2]; *(f32x4*)(rawp + 3 * (size_t)NUP) = G[3]; *(f32x4*)(rawp + 3 * (size_t)NUP + HALF) = V[3]; }
.LBB0_1001:
	s_or_b64 exec, exec, s[42:43]
	v_pk_fma_f32 v[34:35], v[84:85], v[34:35], v[110:111]
	v_pk_mul_f32 v[4:5], v[4:5], v[148:149]
	v_pk_fma_f32 v[38:39], v[86:87], v[38:39], v[112:113]
	v_pk_fma_f32 v[34:35], v[28:29], v[88:89], v[34:35]
	v_pk_mul_f32 v[6:7], v[6:7], v[150:151]
	v_pk_fma_f32 v[38:39], v[30:31], v[90:91], v[38:39]
	v_pk_fma_f32 v[34:35], v[4:5], v[80:81], v[34:35]
	v_pk_fma_f32 v[38:39], v[6:7], v[82:83], v[38:39]
	v_pk_mul_f32 v[40:41], v[34:35], s[86:87] op_sel_hi:[1,0]
	v_pk_mul_f32 v[42:43], v[38:39], s[86:87] op_sel_hi:[1,0]
	v_exp_f32_e32 v40, v40
	v_exp_f32_e32 v41, v41
	v_exp_f32_e32 v42, v42
	v_exp_f32_e32 v43, v43
	v_pk_fma_f32 v[32:33], v[92:93], v[32:33], v[114:115]
	v_pk_add_f32 v[40:41], v[40:41], 1.0 op_sel_hi:[1,0]
	v_pk_mul_f32 v[0:1], v[0:1], v[148:149]
	v_rcp_f32_e32 v40, v40
	v_rcp_f32_e32 v41, v41
	v_pk_add_f32 v[42:43], v[42:43], 1.0 op_sel_hi:[1,0]
	v_pk_fma_f32 v[36:37], v[94:95], v[36:37], v[116:117]
	v_rcp_f32_e32 v42, v42
	v_rcp_f32_e32 v43, v43
	v_pk_fma_f32 v[32:33], v[20:21], v[106:107], v[32:33]
	v_pk_mul_f32 v[2:3], v[2:3], v[150:151]
	v_pk_fma_f32 v[36:37], v[22:23], v[108:109], v[36:37]
	v_pk_fma_f32 v[32:33], v[0:1], v[76:77], v[32:33]
	v_pk_mul_f32 v[34:35], v[34:35], v[40:41]
	v_pk_fma_f32 v[36:37], v[2:3], v[78:79], v[36:37]
	v_pk_mul_f32 v[32:33], v[32:33], v[34:35]
	v_pk_mul_f32 v[34:35], v[38:39], v[42:43]
	v_cvt_pk_bf16_f32 v72, v32, v33
	s_nop 0
	v_pk_mul_f32 v[34:35], v[36:37], v[34:35]
	s_nop 0
	v_cvt_pk_bf16_f32 v73, v34, v35
	s_and_saveexec_b64 s[42:43], s[8:9]
	s_cbranch_execz .LBB0_1003
	v_add_u32_e32 v34, 0x81, v186
	v_mov_b64_e32 v[32:33], s[34:35]
	v_mad_i64_i32 v[32:33], s[48:49], v34, s26, v[32:33]
	v_lshl_add_u64 v[32:33], s[54:55], 1, v[32:33]
	v_lshl_add_u64 v[32:33], v[32:33], 0, s[36:37]
	v_lshl_add_u64 v[32:33], v[178:179], 1, v[32:33]
	global_store_dwordx4 v[32:33], v[70:73], off nt
.LBB0_1003:
	s_or_b64 exec, exec, s[42:43]
	v_pk_fma_f32 v[32:33], v[30:31], v[86:87], v[112:113]
	v_pk_fma_f32 v[34:35], v[28:29], v[84:85], v[110:111]
	v_pk_fma_f32 v[32:33], v[6:7], v[90:91], v[32:33]
	v_pk_fma_f32 v[34:35], v[4:5], v[88:89], v[34:35]
	v_pk_fma_f32 v[32:33], v[26:27], v[82:83], v[32:33]
	v_pk_fma_f32 v[34:35], v[24:25], v[80:81], v[34:35]
	v_pk_mul_f32 v[50:51], v[32:33], s[86:87] op_sel_hi:[1,0]
	v_pk_mul_f32 v[48:49], v[34:35], s[86:87] op_sel_hi:[1,0]
	v_exp_f32_e32 v50, v50
	v_exp_f32_e32 v51, v51
	v_exp_f32_e32 v48, v48
	v_exp_f32_e32 v49, v49
	v_pk_fma_f32 v[36:37], v[22:23], v[94:95], v[116:117]
	v_pk_add_f32 v[50:51], v[50:51], 1.0 op_sel_hi:[1,0]
	v_pk_fma_f32 v[42:43], v[4:5], v[84:85], v[110:111]
	v_rcp_f32_e32 v50, v50
	v_rcp_f32_e32 v51, v51
	v_pk_fma_f32 v[36:37], v[2:3], v[108:109], v[36:37]
	v_pk_fma_f32 v[42:43], v[24:25], v[88:89], v[42:43]
	v_pk_add_f32 v[48:49], v[48:49], 1.0 op_sel_hi:[1,0]
	v_pk_fma_f32 v[36:37], v[14:15], v[78:79], v[36:37]
	v_pk_fma_f32 v[42:43], v[16:17], v[80:81], v[42:43]
	v_rcp_f32_e32 v48, v48
	v_rcp_f32_e32 v49, v49
	v_pk_mul_f32 v[32:33], v[32:33], v[50:51]
	v_pk_fma_f32 v[38:39], v[20:21], v[92:93], v[114:115]
	v_pk_mul_f32 v[32:33], v[36:37], v[32:33]
	v_pk_mul_f32 v[36:37], v[42:43], s[86:87] op_sel_hi:[1,0]
	v_pk_fma_f32 v[38:39], v[0:1], v[106:107], v[38:39]
	v_exp_f32_e32 v36, v36
	v_exp_f32_e32 v37, v37
	v_pk_fma_f32 v[38:39], v[12:13], v[76:77], v[38:39]
	v_pk_fma_f32 v[40:41], v[6:7], v[86:87], v[112:113]
	v_pk_mul_f32 v[34:35], v[34:35], v[48:49]
	v_pk_fma_f32 v[40:41], v[26:27], v[90:91], v[40:41]
	v_pk_mul_f32 v[34:35], v[38:39], v[34:35]
	v_pk_fma_f32 v[40:41], v[18:19], v[82:83], v[40:41]
	v_cvt_pk_bf16_f32 v66, v34, v35
	v_cvt_pk_bf16_f32 v67, v32, v33
	v_add_u32_e32 v34, 0x82, v186
	v_mov_b64_e32 v[32:33], s[34:35]
	v_pk_add_f32 v[36:37], v[36:37], 1.0 op_sel_hi:[1,0]
	v_mad_i64_i32 v[34:35], s[42:43], v34, s26, v[32:33]
	v_pk_mul_f32 v[38:39], v[40:41], s[86:87] op_sel_hi:[1,0]
	v_rcp_f32_e32 v36, v36
	v_rcp_f32_e32 v37, v37
	v_lshl_add_u64 v[34:35], v[34:35], 0, s[56:57]
	v_exp_f32_e32 v38, v38
	v_exp_f32_e32 v39, v39
	v_pk_fma_f32 v[46:47], v[0:1], v[92:93], v[114:115]
	v_lshl_add_u64 v[34:35], v[34:35], 0, s[36:37]
	v_pk_fma_f32 v[46:47], v[12:13], v[106:107], v[46:47]
	v_lshl_add_u64 v[34:35], v[34:35], 0, v[102:103]
	v_pk_fma_f32 v[46:47], v[8:9], v[76:77], v[46:47]
	global_store_dwordx4 v[34:35], v[64:67], off nt
	v_pk_mul_f32 v[34:35], v[42:43], v[36:37]
	v_pk_add_f32 v[38:39], v[38:39], 1.0 op_sel_hi:[1,0]
	v_pk_mul_f32 v[34:35], v[46:47], v[34:35]
	v_rcp_f32_e32 v38, v38
	v_rcp_f32_e32 v39, v39
	v_cvt_pk_bf16_f32 v70, v34, v35
	v_add_u32_e32 v34, 0x83, v186
	v_mad_i64_i32 v[32:33], s[42:43], v34, s26, v[32:33]
	v_pk_fma_f32 v[44:45], v[2:3], v[94:95], v[116:117]
	v_lshl_add_u64 v[32:33], v[32:33], 0, s[56:57]
	v_pk_fma_f32 v[44:45], v[14:15], v[108:109], v[44:45]
	v_lshl_add_u64 v[32:33], v[32:33], 0, s[36:37]
	v_pk_fma_f32 v[44:45], v[10:11], v[78:79], v[44:45]
	v_pk_mul_f32 v[36:37], v[40:41], v[38:39]
	v_lshl_add_u64 v[32:33], v[32:33], 0, v[102:103]
	v_pk_mul_f32 v[36:37], v[44:45], v[36:37]
	v_cmp_lt_i32_e32 vcc, 14, v227
	v_cvt_pk_bf16_f32 v71, v36, v37
	global_store_dwordx4 v[32:33], v[68:71], off nt
	v_lshl_add_u64 v[32:33], v[118:119], 0, 16
	s_mov_b64 s[48:49], 0
	s_and_saveexec_b64 s[42:43], vcc
	s_xor_b64 s[42:43], exec, s[42:43]
	s_cbranch_execz .LBB0_1005
	v_add_co_u32_e32 v0, vcc, 0x16000, v32
	s_mov_b64 s[48:49], exec
	s_nop 0
	v_addc_co_u32_e32 v1, vcc, 0, v33, vcc
	global_store_dwordx4 v[0:1], v[24:27], off nt

;     __device__ __forceinline__ void operator()(const f32x4 (&acc)[2][2][4][2], const Unit& u, int wr, int wc, int fr, int fq) const {
;     ...
;                 if (fr == 0) { *(f32x4*)(rawp) = G[0]; *(f32x4*)(rawp + HALF) = V[0]; *(f32x4*)(rawp + NUP) = G[1]; *(f32x4*)(rawp + NUP + HALF) = V[1]; }
.LBB0_1008:
	v_cmp_eq_u32_e32 vcc, 0, v227
	s_mov_b64 s[54:55], s[48:49]
	s_and_saveexec_b64 s[56:57], vcc
	s_cbranch_execz .LBB0_1010
	s_or_b64 s[54:55], s[48:49], exec
	global_store_dwordx4 v[32:33], v[28:31], off nt

;     __device__ __forceinline__ void operator()(const f32x4 (&acc)[2][2][4][2], const Unit& u, int wr, int wc, int fr, int fq) const {
;     ...
;                 if (fr == 15) { *(f32x4*)(rawp + 2 * (size_t)NUP) = G[2]; *(f32x4*)(rawp + 2 * (size_t)NUP + HALF) = V[2]; *(f32x4*)(rawp + 3 * (size_t)NUP) = G[3]; *(f32x4*)(rawp + 3 * (size_t)NUP + HALF) = V[3]; }
; template <class Epi, class Sched, bool ALIGN_EPI = false, bool SP2 = false>
; __device__ __forceinline__ void gemm_phase(LAS unsigned char* lds, const Gemm g, const Sched& S, const Epi& E, int wid) {
;     ...
;         if (!has_next) break;
; #pragma unroll
;         for (int a = 0; a < 2; ++a)
; #pragma unroll
;             for (int b = 0; b < 2; ++b)
; #pragma unroll
;                 for (int m = 0; m < 4; ++m)
; #pragma unroll
;                     for (int n = 0; n < 2; ++n) acc[a][b][m][n] = (f32x4){0.f, 0.f, 0.f, 0.f};
;         cur = nxt; cA = nA; cB = nB; ++ui;
.LBB0_1011:
	v_lshl_add_u64 v[0:1], v[118:119], 0, v[26:27]
	global_store_dwordx4 v[0:1], v[12:15], off offset:16 nt
	v_lshl_add_u64 v[0:1], v[118:119], 0, v[24:25]
	global_store_dwordx4 v[0:1], v[16:19], off offset:16 nt
	v_lshl_add_u64 v[0:1], v[118:119], 0, v[34:35]
	global_store_dwordx4 v[0:1], v[8:11], off offset:16 nt
	s_or_b64 exec, exec, s[42:43]
	s_andn2_b64 vcc, exec, s[10:11]
	s_mov_b64 s[10:11], -1
	s_cbranch_vccnz .LBB0_964
